# P8 SwiGLU epilogue: scalar exponent-argument multiplies and (1+e)*x fmas packed into v_pk_mul_f32 / v_pk_fma_f32 on an aligned temp block
# baseline (speedup 1.0000x reference)
; DI unsigned pk2(float lo, float hi) { const f32x2 v = {lo, hi}; const hwbf16x2 b = __builtin_convertvector(v, hwbf16x2); return __builtin_bit_cast(unsigned, b); }
; DI float frsq(float x) { return __builtin_amdgcn_rsqf(x); }
; DI float fsilu(float v) { return v * frcp(1.f + __expf(-v)); }
;     DI void operator()(const f32x4 (&acc)[2][2][4][2], const Unit& u, int wr, int wc, int fr, int fq) const {
;     ...
;                 const int row = row0 + ai * HALF + m * 16;
;                 float rs = 1.f, rowacc = 0.f;
;                 if (mode == EPI_STORE || mode == EPI_Q) { if (rscale) rs = rscale[row]; }
;                 if (mode == EPI_SWIGLU) rs = frsq(rowsq[row] * (1.0f / DM) + 1e-6f);
;     ...
;                     } else {
;                         v0 = v0 * rs; v1 = v1 * rs;
;                         u32x2 w; w.x = pk2(fsilu(v0[0]) * v1[0], fsilu(v0[1]) * v1[1]); w.y = pk2(fsilu(v0[2]) * v1[2], fsilu(v0[3]) * v1[3]);
;                         *(u32x2*)(O + (size_t)row * ldc + (col >> 1)) = w;
.LBB0_1023:
	v_lshl_add_u32 v144, s22, 8, v152
	v_ashrrev_i32_e32 v145, 31, v144
	v_lshl_add_u64 v[148:149], v[144:145], 2, s[74:75]
	global_load_dword v236, v[148:149], off
	global_load_dword v237, v[148:149], off offset:64
	global_load_dword v238, v[148:149], off offset:128
	global_load_dword v239, v[148:149], off offset:192
	global_load_dword v240, v[148:149], off offset:512
	global_load_dword v241, v[148:149], off offset:576
	global_load_dword v242, v[148:149], off offset:640
	global_load_dword v243, v[148:149], off offset:704
	v_or_b32_e32 v162, 16, v144
	v_ashrrev_i32_e32 v163, 31, v162
	v_lshl_add_u64 v[170:171], v[162:163], 2, s[74:75]
	v_lshl_or_b32 v150, s40, 8, v154
	v_ashrrev_i32_e32 v150, 1, v150
	v_mov_b64_e32 v[146:147], s[44:45]
	v_ashrrev_i32_e32 v151, 31, v150
	v_mad_i64_i32 v[160:161], s[24:25], v144, s39, v[146:147]
	v_lshlrev_b64 v[150:151], 1, v[150:151]
	v_lshl_add_u64 v[160:161], v[160:161], 0, v[150:151]
	s_andn2_b64 vcc, exec, s[4:5]
	s_mov_b64 s[4:5], -1
	s_waitcnt vmcnt(7)
	v_fmamk_f32 v244, v236, 0x3a000000, v158
	v_rsq_f32_e32 v246, v244
	s_nop 0
	v_mul_f32_e32 v246, 0xbfb8aa3b, v246
	v_pk_mul_f32 v[248:249], v[124:125], v[246:247] op_sel_hi:[1,0]
	v_pk_mul_f32 v[250:251], v[126:127], v[246:247] op_sel_hi:[1,0]
	v_pk_mul_f32 v[252:253], v[116:117], v[246:247] op_sel_hi:[1,0]
	v_pk_mul_f32 v[254:255], v[118:119], v[246:247] op_sel_hi:[1,0]
	v_exp_f32_e32 v248, v248
	v_exp_f32_e32 v249, v249
	v_exp_f32_e32 v250, v250
	v_exp_f32_e32 v251, v251
	v_exp_f32_e32 v252, v252
	v_exp_f32_e32 v253, v253
	v_exp_f32_e32 v254, v254
	v_exp_f32_e32 v255, v255
	v_pk_fma_f32 v[248:249], v[248:249], v[244:245], v[244:245] op_sel_hi:[1,0,0]
	v_pk_fma_f32 v[250:251], v[250:251], v[244:245], v[244:245] op_sel_hi:[1,0,0]
	v_pk_fma_f32 v[252:253], v[252:253], v[244:245], v[244:245] op_sel_hi:[1,0,0]
	v_pk_fma_f32 v[254:255], v[254:255], v[244:245], v[244:245] op_sel_hi:[1,0,0]
	v_rcp_f32_e32 v164, v248
	v_rcp_f32_e32 v165, v249
	v_rcp_f32_e32 v172, v250
	v_rcp_f32_e32 v173, v251
	v_rcp_f32_e32 v174, v252
	v_rcp_f32_e32 v175, v253
	v_rcp_f32_e32 v176, v254
	v_rcp_f32_e32 v177, v255
	v_pk_mul_f32 v[124:125], v[124:125], v[164:165]
	v_pk_mul_f32 v[126:127], v[126:127], v[172:173]
	v_pk_mul_f32 v[116:117], v[116:117], v[174:175]
	v_pk_mul_f32 v[118:119], v[118:119], v[176:177]
	v_pk_mul_f32 v[120:121], v[120:121], v[124:125]
	v_pk_mul_f32 v[122:123], v[122:123], v[126:127]
	v_pk_mul_f32 v[112:113], v[112:113], v[116:117]
	v_pk_mul_f32 v[114:115], v[114:115], v[118:119]
	v_cvt_pk_bf16_f32 v116, v120, v121
	v_cvt_pk_bf16_f32 v117, v122, v123
	v_cvt_pk_bf16_f32 v112, v112, v113
	v_cvt_pk_bf16_f32 v113, v114, v115
	global_store_dwordx2 v[160:161], v[116:117], off
	global_store_dwordx2 v[160:161], v[112:113], off offset:128
	v_or_b32_e32 v112, 32, v144
	v_mad_i64_i32 v[114:115], s[24:25], v162, s39, v[146:147]
	v_lshl_add_u64 v[114:115], v[114:115], 0, v[150:151]
	s_waitcnt vmcnt(8)
	v_fmamk_f32 v244, v237, 0x3a000000, v158
	v_rsq_f32_e32 v246, v244
	v_ashrrev_i32_e32 v113, 31, v112
	v_lshl_add_u64 v[118:119], v[112:113], 2, s[74:75]
	v_mul_f32_e32 v246, 0xbfb8aa3b, v246
	v_pk_mul_f32 v[248:249], v[108:109], v[246:247] op_sel_hi:[1,0]
	v_pk_mul_f32 v[250:251], v[110:111], v[246:247] op_sel_hi:[1,0]
	v_pk_mul_f32 v[252:253], v[100:101], v[246:247] op_sel_hi:[1,0]
	v_pk_mul_f32 v[254:255], v[102:103], v[246:247] op_sel_hi:[1,0]
	v_exp_f32_e32 v248, v248
	v_exp_f32_e32 v249, v249
	v_exp_f32_e32 v250, v250
	v_exp_f32_e32 v251, v251
	v_exp_f32_e32 v252, v252
	v_exp_f32_e32 v253, v253
	v_exp_f32_e32 v254, v254
	v_exp_f32_e32 v255, v255
	v_pk_fma_f32 v[248:249], v[248:249], v[244:245], v[244:245] op_sel_hi:[1,0,0]
	v_pk_fma_f32 v[250:251], v[250:251], v[244:245], v[244:245] op_sel_hi:[1,0,0]
	v_pk_fma_f32 v[252:253], v[252:253], v[244:245], v[244:245] op_sel_hi:[1,0,0]
	v_pk_fma_f32 v[254:255], v[254:255], v[244:245], v[244:245] op_sel_hi:[1,0,0]
	v_rcp_f32_e32 v116, v248
	v_rcp_f32_e32 v117, v249
	v_rcp_f32_e32 v120, v250
	v_rcp_f32_e32 v121, v251
	v_rcp_f32_e32 v122, v252
	v_rcp_f32_e32 v123, v253
	v_rcp_f32_e32 v124, v254
	v_rcp_f32_e32 v125, v255
	v_pk_mul_f32 v[108:109], v[108:109], v[116:117]
	v_pk_mul_f32 v[110:111], v[110:111], v[120:121]
	v_pk_mul_f32 v[100:101], v[100:101], v[122:123]
	v_pk_mul_f32 v[102:103], v[102:103], v[124:125]
	v_pk_mul_f32 v[104:105], v[104:105], v[108:109]
	v_pk_mul_f32 v[106:107], v[106:107], v[110:111]
	v_pk_mul_f32 v[96:97], v[96:97], v[100:101]
	v_pk_mul_f32 v[98:99], v[98:99], v[102:103]
	v_cvt_pk_bf16_f32 v100, v104, v105
	v_cvt_pk_bf16_f32 v101, v106, v107
	v_cvt_pk_bf16_f32 v96, v96, v97
	v_cvt_pk_bf16_f32 v97, v98, v99
	global_store_dwordx2 v[114:115], v[100:101], off
	global_store_dwordx2 v[114:115], v[96:97], off offset:128
	v_or_b32_e32 v96, 48, v144
	v_mad_i64_i32 v[98:99], s[24:25], v112, s39, v[146:147]
	v_lshl_add_u64 v[98:99], v[98:99], 0, v[150:151]
	s_waitcnt vmcnt(9)
; DI unsigned pk2(float lo, float hi) { const f32x2 v = {lo, hi}; const hwbf16x2 b = __builtin_convertvector(v, hwbf16x2); return __builtin_bit_cast(unsigned, b); }
; DI float frsq(float x) { return __builtin_amdgcn_rsqf(x); }
; DI float fsilu(float v) { return v * frcp(1.f + __expf(-v)); }
;     DI void operator()(const f32x4 (&acc)[2][2][4][2], const Unit& u, int wr, int wc, int fr, int fq) const {
;     ...
;                 const int row = row0 + ai * HALF + m * 16;
;                 float rs = 1.f, rowacc = 0.f;
;                 if (mode == EPI_STORE || mode == EPI_Q) { if (rscale) rs = rscale[row]; }
;                 if (mode == EPI_SWIGLU) rs = frsq(rowsq[row] * (1.0f / DM) + 1e-6f);
;     ...
;                     } else {
;                         v0 = v0 * rs; v1 = v1 * rs;
;                         u32x2 w; w.x = pk2(fsilu(v0[0]) * v1[0], fsilu(v0[1]) * v1[1]); w.y = pk2(fsilu(v0[2]) * v1[2], fsilu(v0[3]) * v1[3]);
;                         *(u32x2*)(O + (size_t)row * ldc + (col >> 1)) = w;
	v_fmamk_f32 v244, v238, 0x3a000000, v158
	v_rsq_f32_e32 v246, v244
	v_ashrrev_i32_e32 v97, 31, v96
	v_lshl_add_u64 v[102:103], v[96:97], 2, s[74:75]
	v_mul_f32_e32 v246, 0xbfb8aa3b, v246
	v_pk_mul_f32 v[248:249], v[92:93], v[246:247] op_sel_hi:[1,0]
	v_pk_mul_f32 v[250:251], v[94:95], v[246:247] op_sel_hi:[1,0]
	v_pk_mul_f32 v[252:253], v[84:85], v[246:247] op_sel_hi:[1,0]
	v_pk_mul_f32 v[254:255], v[86:87], v[246:247] op_sel_hi:[1,0]
	v_exp_f32_e32 v248, v248
	v_exp_f32_e32 v249, v249
	v_exp_f32_e32 v250, v250
	v_exp_f32_e32 v251, v251
	v_exp_f32_e32 v252, v252
	v_exp_f32_e32 v253, v253
	v_exp_f32_e32 v254, v254
	v_exp_f32_e32 v255, v255
	v_pk_fma_f32 v[248:249], v[248:249], v[244:245], v[244:245] op_sel_hi:[1,0,0]
	v_pk_fma_f32 v[250:251], v[250:251], v[244:245], v[244:245] op_sel_hi:[1,0,0]
	v_pk_fma_f32 v[252:253], v[252:253], v[244:245], v[244:245] op_sel_hi:[1,0,0]
	v_pk_fma_f32 v[254:255], v[254:255], v[244:245], v[244:245] op_sel_hi:[1,0,0]
	v_rcp_f32_e32 v100, v248
	v_rcp_f32_e32 v101, v249
	v_rcp_f32_e32 v104, v250
	v_rcp_f32_e32 v105, v251
	v_rcp_f32_e32 v106, v252
	v_rcp_f32_e32 v107, v253
	v_rcp_f32_e32 v108, v254
	v_rcp_f32_e32 v109, v255
	v_pk_mul_f32 v[92:93], v[92:93], v[100:101]
	v_pk_mul_f32 v[94:95], v[94:95], v[104:105]
	v_pk_mul_f32 v[84:85], v[84:85], v[106:107]
	v_pk_mul_f32 v[86:87], v[86:87], v[108:109]
	v_pk_mul_f32 v[88:89], v[88:89], v[92:93]
	v_pk_mul_f32 v[90:91], v[90:91], v[94:95]
	v_pk_mul_f32 v[80:81], v[80:81], v[84:85]
	v_pk_mul_f32 v[82:83], v[82:83], v[86:87]
	v_cvt_pk_bf16_f32 v84, v88, v89
	v_cvt_pk_bf16_f32 v85, v90, v91
	v_cvt_pk_bf16_f32 v80, v80, v81
	v_cvt_pk_bf16_f32 v81, v82, v83
	global_store_dwordx2 v[98:99], v[84:85], off
	global_store_dwordx2 v[98:99], v[80:81], off offset:128
	v_mad_i64_i32 v[82:83], s[24:25], v96, s39, v[146:147]
	v_lshl_add_u64 v[82:83], v[82:83], 0, v[150:151]
	s_waitcnt vmcnt(10)
	v_fmamk_f32 v244, v239, 0x3a000000, v158
	v_rsq_f32_e32 v246, v244
	s_nop 0
	v_mul_f32_e32 v246, 0xbfb8aa3b, v246
	v_pk_mul_f32 v[248:249], v[76:77], v[246:247] op_sel_hi:[1,0]
	v_pk_mul_f32 v[250:251], v[78:79], v[246:247] op_sel_hi:[1,0]
	v_pk_mul_f32 v[252:253], v[68:69], v[246:247] op_sel_hi:[1,0]
	v_pk_mul_f32 v[254:255], v[70:71], v[246:247] op_sel_hi:[1,0]
	v_exp_f32_e32 v248, v248
	v_exp_f32_e32 v249, v249
	v_exp_f32_e32 v250, v250
	v_exp_f32_e32 v251, v251
	v_exp_f32_e32 v252, v252
	v_exp_f32_e32 v253, v253
	v_exp_f32_e32 v254, v254
	v_exp_f32_e32 v255, v255
	v_pk_fma_f32 v[248:249], v[248:249], v[244:245], v[244:245] op_sel_hi:[1,0,0]
	v_pk_fma_f32 v[250:251], v[250:251], v[244:245], v[244:245] op_sel_hi:[1,0,0]
	v_pk_fma_f32 v[252:253], v[252:253], v[244:245], v[244:245] op_sel_hi:[1,0,0]
	v_pk_fma_f32 v[254:255], v[254:255], v[244:245], v[244:245] op_sel_hi:[1,0,0]
	v_rcp_f32_e32 v80, v248
	v_rcp_f32_e32 v81, v249
	v_rcp_f32_e32 v84, v250
	v_rcp_f32_e32 v85, v251
	v_rcp_f32_e32 v86, v252
	v_rcp_f32_e32 v87, v253
	v_rcp_f32_e32 v88, v254
	v_rcp_f32_e32 v89, v255
	v_pk_mul_f32 v[76:77], v[76:77], v[80:81]
	v_pk_mul_f32 v[78:79], v[78:79], v[84:85]
	v_pk_mul_f32 v[68:69], v[68:69], v[86:87]
	v_pk_mul_f32 v[70:71], v[70:71], v[88:89]
	v_pk_mul_f32 v[72:73], v[72:73], v[76:77]
	v_pk_mul_f32 v[74:75], v[74:75], v[78:79]
	v_pk_mul_f32 v[64:65], v[64:65], v[68:69]
	v_pk_mul_f32 v[66:67], v[66:67], v[70:71]
	v_cvt_pk_bf16_f32 v68, v72, v73
	v_cvt_pk_bf16_f32 v69, v74, v75
	v_cvt_pk_bf16_f32 v64, v64, v65
	v_cvt_pk_bf16_f32 v65, v66, v67
	global_store_dwordx2 v[82:83], v[68:69], off
	global_store_dwordx2 v[82:83], v[64:65], off offset:128
	v_add_u32_e32 v65, 0x80, v144
	v_mad_i64_i32 v[66:67], s[24:25], v65, s39, v[146:147]
	v_lshl_add_u64 v[66:67], v[66:67], 0, v[150:151]
	s_waitcnt vmcnt(11)
	v_fmamk_f32 v244, v240, 0x3a000000, v158
	v_rsq_f32_e32 v246, v244
	s_nop 0
	v_mul_f32_e32 v246, 0xbfb8aa3b, v246
	v_pk_mul_f32 v[248:249], v[60:61], v[246:247] op_sel_hi:[1,0]
	v_pk_mul_f32 v[250:251], v[62:63], v[246:247] op_sel_hi:[1,0]
	v_pk_mul_f32 v[252:253], v[52:53], v[246:247] op_sel_hi:[1,0]
	v_pk_mul_f32 v[254:255], v[54:55], v[246:247] op_sel_hi:[1,0]
	v_exp_f32_e32 v248, v248
	v_exp_f32_e32 v249, v249
	v_exp_f32_e32 v250, v250
	v_exp_f32_e32 v251, v251
	v_exp_f32_e32 v252, v252
	v_exp_f32_e32 v253, v253
	v_exp_f32_e32 v254, v254
	v_exp_f32_e32 v255, v255
	v_pk_fma_f32 v[248:249], v[248:249], v[244:245], v[244:245] op_sel_hi:[1,0,0]
	v_pk_fma_f32 v[250:251], v[250:251], v[244:245], v[244:245] op_sel_hi:[1,0,0]
	v_pk_fma_f32 v[252:253], v[252:253], v[244:245], v[244:245] op_sel_hi:[1,0,0]
	v_pk_fma_f32 v[254:255], v[254:255], v[244:245], v[244:245] op_sel_hi:[1,0,0]
	v_rcp_f32_e32 v64, v248
	v_rcp_f32_e32 v65, v249
	v_rcp_f32_e32 v68, v250
	v_rcp_f32_e32 v69, v251
	v_rcp_f32_e32 v70, v252
	v_rcp_f32_e32 v71, v253
	v_rcp_f32_e32 v72, v254
	v_rcp_f32_e32 v73, v255
	v_pk_mul_f32 v[60:61], v[60:61], v[64:65]
	v_pk_mul_f32 v[62:63], v[62:63], v[68:69]
	v_pk_mul_f32 v[52:53], v[52:53], v[70:71]
	v_pk_mul_f32 v[54:55], v[54:55], v[72:73]
	v_pk_mul_f32 v[56:57], v[56:57], v[60:61]
	v_pk_mul_f32 v[58:59], v[58:59], v[62:63]
	v_pk_mul_f32 v[48:49], v[48:49], v[52:53]
	v_pk_mul_f32 v[50:51], v[50:51], v[54:55]
	v_cvt_pk_bf16_f32 v52, v56, v57
	v_cvt_pk_bf16_f32 v53, v58, v59
	v_cvt_pk_bf16_f32 v48, v48, v49
	v_cvt_pk_bf16_f32 v49, v50, v51
	global_store_dwordx2 v[66:67], v[52:53], off
	global_store_dwordx2 v[66:67], v[48:49], off offset:128
	v_add_u32_e32 v49, 0x90, v144
	v_mad_i64_i32 v[50:51], s[24:25], v49, s39, v[146:147]
	v_lshl_add_u64 v[50:51], v[50:51], 0, v[150:151]
	s_waitcnt vmcnt(12)
; DI unsigned pk2(float lo, float hi) { const f32x2 v = {lo, hi}; const hwbf16x2 b = __builtin_convertvector(v, hwbf16x2); return __builtin_bit_cast(unsigned, b); }
; DI float frsq(float x) { return __builtin_amdgcn_rsqf(x); }
; DI float fsilu(float v) { return v * frcp(1.f + __expf(-v)); }
;     DI void operator()(const f32x4 (&acc)[2][2][4][2], const Unit& u, int wr, int wc, int fr, int fq) const {
;     ...
;                 const int row = row0 + ai * HALF + m * 16;
;                 float rs = 1.f, rowacc = 0.f;
;                 if (mode == EPI_STORE || mode == EPI_Q) { if (rscale) rs = rscale[row]; }
;                 if (mode == EPI_SWIGLU) rs = frsq(rowsq[row] * (1.0f / DM) + 1e-6f);
;     ...
;                     } else {
;                         v0 = v0 * rs; v1 = v1 * rs;
;                         u32x2 w; w.x = pk2(fsilu(v0[0]) * v1[0], fsilu(v0[1]) * v1[1]); w.y = pk2(fsilu(v0[2]) * v1[2], fsilu(v0[3]) * v1[3]);
;                         *(u32x2*)(O + (size_t)row * ldc + (col >> 1)) = w;
	v_fmamk_f32 v244, v241, 0x3a000000, v158
	v_rsq_f32_e32 v246, v244
	s_nop 0
	v_mul_f32_e32 v246, 0xbfb8aa3b, v246
	v_pk_mul_f32 v[248:249], v[44:45], v[246:247] op_sel_hi:[1,0]
	v_pk_mul_f32 v[250:251], v[46:47], v[246:247] op_sel_hi:[1,0]
	v_pk_mul_f32 v[252:253], v[36:37], v[246:247] op_sel_hi:[1,0]
	v_pk_mul_f32 v[254:255], v[38:39], v[246:247] op_sel_hi:[1,0]
	v_exp_f32_e32 v248, v248
	v_exp_f32_e32 v249, v249
	v_exp_f32_e32 v250, v250
	v_exp_f32_e32 v251, v251
	v_exp_f32_e32 v252, v252
	v_exp_f32_e32 v253, v253
	v_exp_f32_e32 v254, v254
	v_exp_f32_e32 v255, v255
	v_pk_fma_f32 v[248:249], v[248:249], v[244:245], v[244:245] op_sel_hi:[1,0,0]
	v_pk_fma_f32 v[250:251], v[250:251], v[244:245], v[244:245] op_sel_hi:[1,0,0]
	v_pk_fma_f32 v[252:253], v[252:253], v[244:245], v[244:245] op_sel_hi:[1,0,0]
	v_pk_fma_f32 v[254:255], v[254:255], v[244:245], v[244:245] op_sel_hi:[1,0,0]
	v_rcp_f32_e32 v48, v248
	v_rcp_f32_e32 v49, v249
	v_rcp_f32_e32 v52, v250
	v_rcp_f32_e32 v53, v251
	v_rcp_f32_e32 v54, v252
	v_rcp_f32_e32 v55, v253
	v_rcp_f32_e32 v56, v254
	v_rcp_f32_e32 v57, v255
	v_pk_mul_f32 v[44:45], v[44:45], v[48:49]
	v_pk_mul_f32 v[46:47], v[46:47], v[52:53]
	v_pk_mul_f32 v[36:37], v[36:37], v[54:55]
	v_pk_mul_f32 v[38:39], v[38:39], v[56:57]
	v_pk_mul_f32 v[40:41], v[40:41], v[44:45]
	v_pk_mul_f32 v[42:43], v[42:43], v[46:47]
	v_pk_mul_f32 v[32:33], v[32:33], v[36:37]
	v_pk_mul_f32 v[34:35], v[34:35], v[38:39]
	v_cvt_pk_bf16_f32 v36, v40, v41
	v_cvt_pk_bf16_f32 v37, v42, v43
	v_cvt_pk_bf16_f32 v32, v32, v33
	v_cvt_pk_bf16_f32 v33, v34, v35
	global_store_dwordx2 v[50:51], v[36:37], off
	global_store_dwordx2 v[50:51], v[32:33], off offset:128
	v_add_u32_e32 v33, 0xa0, v144
	v_mad_i64_i32 v[34:35], s[24:25], v33, s39, v[146:147]
	v_lshl_add_u64 v[34:35], v[34:35], 0, v[150:151]
	s_waitcnt vmcnt(13)
	v_fmamk_f32 v244, v242, 0x3a000000, v158
	v_rsq_f32_e32 v246, v244
	s_nop 0
	v_mul_f32_e32 v246, 0xbfb8aa3b, v246
	v_pk_mul_f32 v[248:249], v[28:29], v[246:247] op_sel_hi:[1,0]
	v_pk_mul_f32 v[250:251], v[30:31], v[246:247] op_sel_hi:[1,0]
	v_pk_mul_f32 v[252:253], v[20:21], v[246:247] op_sel_hi:[1,0]
	v_pk_mul_f32 v[254:255], v[22:23], v[246:247] op_sel_hi:[1,0]
	v_exp_f32_e32 v248, v248
	v_exp_f32_e32 v249, v249
	v_exp_f32_e32 v250, v250
	v_exp_f32_e32 v251, v251
	v_exp_f32_e32 v252, v252
	v_exp_f32_e32 v253, v253
	v_exp_f32_e32 v254, v254
	v_exp_f32_e32 v255, v255
	v_pk_fma_f32 v[248:249], v[248:249], v[244:245], v[244:245] op_sel_hi:[1,0,0]
	v_pk_fma_f32 v[250:251], v[250:251], v[244:245], v[244:245] op_sel_hi:[1,0,0]
	v_pk_fma_f32 v[252:253], v[252:253], v[244:245], v[244:245] op_sel_hi:[1,0,0]
	v_pk_fma_f32 v[254:255], v[254:255], v[244:245], v[244:245] op_sel_hi:[1,0,0]
	v_rcp_f32_e32 v32, v248
	v_rcp_f32_e32 v33, v249
	v_rcp_f32_e32 v36, v250
	v_rcp_f32_e32 v37, v251
	v_rcp_f32_e32 v38, v252
	v_rcp_f32_e32 v39, v253
	v_rcp_f32_e32 v40, v254
	v_rcp_f32_e32 v41, v255
	v_pk_mul_f32 v[28:29], v[28:29], v[32:33]
	v_pk_mul_f32 v[30:31], v[30:31], v[36:37]
	v_pk_mul_f32 v[20:21], v[20:21], v[38:39]
	v_pk_mul_f32 v[22:23], v[22:23], v[40:41]
	v_pk_mul_f32 v[24:25], v[24:25], v[28:29]
	v_pk_mul_f32 v[26:27], v[26:27], v[30:31]
	v_pk_mul_f32 v[16:17], v[16:17], v[20:21]
	v_pk_mul_f32 v[18:19], v[18:19], v[22:23]
	v_cvt_pk_bf16_f32 v20, v24, v25
	v_cvt_pk_bf16_f32 v21, v26, v27
	v_cvt_pk_bf16_f32 v16, v16, v17
	v_cvt_pk_bf16_f32 v17, v18, v19
	global_store_dwordx2 v[34:35], v[20:21], off
	global_store_dwordx2 v[34:35], v[16:17], off offset:128
	v_add_u32_e32 v17, 0xb0, v144
	v_mad_i64_i32 v[18:19], s[24:25], v17, s39, v[146:147]
	v_lshl_add_u64 v[18:19], v[18:19], 0, v[150:151]
	s_waitcnt vmcnt(14)
	v_fmamk_f32 v244, v243, 0x3a000000, v158
	v_rsq_f32_e32 v246, v244
	s_nop 0
	v_mul_f32_e32 v246, 0xbfb8aa3b, v246
	v_pk_mul_f32 v[248:249], v[12:13], v[246:247] op_sel_hi:[1,0]
	v_pk_mul_f32 v[250:251], v[14:15], v[246:247] op_sel_hi:[1,0]
	v_pk_mul_f32 v[252:253], v[4:5], v[246:247] op_sel_hi:[1,0]
	v_pk_mul_f32 v[254:255], v[6:7], v[246:247] op_sel_hi:[1,0]
	v_exp_f32_e32 v248, v248
	v_exp_f32_e32 v249, v249
	v_exp_f32_e32 v250, v250
	v_exp_f32_e32 v251, v251
	v_exp_f32_e32 v252, v252
	v_exp_f32_e32 v253, v253
	v_exp_f32_e32 v254, v254
	v_exp_f32_e32 v255, v255
	v_pk_fma_f32 v[248:249], v[248:249], v[244:245], v[244:245] op_sel_hi:[1,0,0]
	v_pk_fma_f32 v[250:251], v[250:251], v[244:245], v[244:245] op_sel_hi:[1,0,0]
	v_pk_fma_f32 v[252:253], v[252:253], v[244:245], v[244:245] op_sel_hi:[1,0,0]
	v_pk_fma_f32 v[254:255], v[254:255], v[244:245], v[244:245] op_sel_hi:[1,0,0]
	v_rcp_f32_e32 v16, v248
	v_rcp_f32_e32 v17, v249
	v_rcp_f32_e32 v20, v250
	v_rcp_f32_e32 v21, v251
	v_rcp_f32_e32 v22, v252
	v_rcp_f32_e32 v23, v253
	v_rcp_f32_e32 v24, v254
	v_rcp_f32_e32 v25, v255
	v_pk_mul_f32 v[12:13], v[12:13], v[16:17]
	v_pk_mul_f32 v[14:15], v[14:15], v[20:21]
	v_pk_mul_f32 v[4:5], v[4:5], v[22:23]
	v_pk_mul_f32 v[6:7], v[6:7], v[24:25]
	v_pk_mul_f32 v[8:9], v[8:9], v[12:13]
	v_pk_mul_f32 v[10:11], v[10:11], v[14:15]
	v_pk_mul_f32 v[0:1], v[0:1], v[4:5]
	v_pk_mul_f32 v[2:3], v[2:3], v[6:7]
	v_cvt_pk_bf16_f32 v4, v8, v9
	v_cvt_pk_bf16_f32 v5, v10, v11
	v_cvt_pk_bf16_f32 v0, v0, v1
	v_cvt_pk_bf16_f32 v1, v2, v3
	global_store_dwordx2 v[18:19], v[4:5], off
	global_store_dwordx2 v[18:19], v[0:1], off offset:128
	s_cbranch_vccnz .LBB0_1016
	s_andn2_b64 vcc, exec, s[6:7]
	s_cbranch_vccnz .LBB0_1015
	s_barrier
	s_branch .LBB0_1015
